# grid barrier: XCD leader bumps generation before its own L1 invalidate
# speedup vs baseline: 1.0302x; 1.0024x over previous
.LBB0_56:
	s_or_b64 exec, exec, s[8:9]
	s_mov_b64 s[8:9], exec
	v_mbcnt_lo_u32_b32 v1, s8, 0
	v_mbcnt_hi_u32_b32 v1, s9, v1
	v_cmp_eq_u32_e32 vcc, 0, v1
	s_waitcnt vmcnt(0)
	s_and_saveexec_b64 s[10:11], vcc
	s_cbranch_execz .LBB0_58
	s_bcnt1_i32_b64 s8, s[8:9]
	v_mov_b32_e32 v1, 0x2000
	v_mov_b32_e32 v2, s8
	global_atomic_add v1, v2, s[2:3] offset:1024
.LBB0_58:
	s_or_b64 exec, exec, s[10:11]
	buffer_inv sc1
	s_waitcnt vmcnt(0)

.LBB0_175:
	s_or_b64 exec, exec, s[4:5]
	s_mov_b64 s[4:5], exec
	v_mbcnt_lo_u32_b32 v1, s4, 0
	v_mbcnt_hi_u32_b32 v1, s5, v1
	v_cmp_eq_u32_e32 vcc, 0, v1
	s_waitcnt vmcnt(0)
	s_and_saveexec_b64 s[10:11], vcc
	s_cbranch_execz .LBB0_177
	s_bcnt1_i32_b64 s4, s[4:5]
	v_mov_b32_e32 v1, 0
	v_mov_b32_e32 v2, s4
	global_atomic_add v1, v2, s[8:9]

.LBB0_427:
	s_or_b64 exec, exec, s[2:3]
	s_mov_b64 s[2:3], exec
	v_mbcnt_lo_u32_b32 v1, s2, 0
	v_mbcnt_hi_u32_b32 v1, s3, v1
	v_cmp_eq_u32_e32 vcc, 0, v1
	s_waitcnt vmcnt(0)
	s_and_saveexec_b64 s[8:9], vcc
	s_cbranch_execz .LBB0_429
	s_bcnt1_i32_b64 s2, s[2:3]
	v_mov_b32_e32 v1, 0
	v_mov_b32_e32 v2, s2
	global_atomic_add v1, v2, s[4:5]
.LBB0_429:
	s_or_b64 exec, exec, s[8:9]
	buffer_inv sc1
	s_waitcnt vmcnt(0)

.LBB0_565:
	s_or_b64 exec, exec, s[4:5]
	s_mov_b64 s[4:5], exec
	v_mbcnt_lo_u32_b32 v1, s4, 0
	v_mbcnt_hi_u32_b32 v1, s5, v1
	v_cmp_eq_u32_e32 vcc, 0, v1
	s_waitcnt vmcnt(0)
	s_and_saveexec_b64 s[6:7], vcc
	s_cbranch_execz .LBB0_567
	s_bcnt1_i32_b64 s4, s[4:5]
	v_mov_b32_e32 v1, 0x2000
	v_mov_b32_e32 v2, s4
	global_atomic_add v1, v2, s[2:3] offset:1024
.LBB0_567:
	s_or_b64 exec, exec, s[6:7]
	buffer_inv sc1
	s_waitcnt vmcnt(0)

.LBB0_712:
	s_or_b64 exec, exec, s[6:7]
	s_mov_b64 s[6:7], exec
	v_mbcnt_lo_u32_b32 v1, s6, 0
	v_mbcnt_hi_u32_b32 v1, s7, v1
	v_cmp_eq_u32_e32 vcc, 0, v1
	s_waitcnt vmcnt(0)
	s_and_saveexec_b64 s[8:9], vcc
	s_cbranch_execz .LBB0_714
	s_bcnt1_i32_b64 s6, s[6:7]
	v_mov_b32_e32 v1, 0x2000
	v_mov_b32_e32 v2, s6
	global_atomic_add v1, v2, s[4:5] offset:1024

.LBB0_807:
	s_or_b64 exec, exec, s[4:5]
	s_mov_b64 s[4:5], exec
	v_mbcnt_lo_u32_b32 v1, s4, 0
	v_mbcnt_hi_u32_b32 v1, s5, v1
	v_cmp_eq_u32_e32 vcc, 0, v1
	s_waitcnt vmcnt(0)
	s_and_saveexec_b64 s[8:9], vcc
	s_cbranch_execz .LBB0_809
	s_bcnt1_i32_b64 s4, s[4:5]
	v_mov_b32_e32 v1, 0x2000
	v_mov_b32_e32 v2, s4
	global_atomic_add v1, v2, s[2:3] offset:1024
